# 8-way K-split of the FFN-down sample tiles (partials in the dead Y region) on top of the lazy finalize; wt tiles and cache copy on blocks 128..255
# speedup vs baseline: 1.0043x; 1.0043x over previous
.LBB0_62:
	s_or_b64 exec, exec, s[0:1]
	v_ashrrev_i32_e32 v0, 6, v2
	v_readlane_b32 s0, v244, 6
	s_nop 1
	v_add_u32_e32 v136, s0, v0
	s_movk_i32 s0, 0x4400
	v_cmp_gt_i32_e32 vcc, s0, v136
	s_and_saveexec_b64 s[8:9], vcc
	s_cbranch_execz .LBB0_68
	v_and_b32_e32 v4, 63, v2
	v_readlane_b32 s0, v243, 19
	v_readlane_b32 s1, v243, 20
	v_readlane_b32 s34, v240, 23
	v_readlane_b32 s10, v243, 54
	v_readlane_b32 s11, v243, 55
	v_lshlrev_b32_e32 v0, 3, v4
	v_mov_b32_e32 v1, v137
	v_lshlrev_b32_e32 v2, 4, v4
	v_mov_b32_e32 v3, v137
	s_cmp_eq_u32 s34, 6
	s_cselect_b32 s0, s0, s10
	s_cselect_b32 s1, s1, s11
	v_lshl_add_u64 v[0:1], s[96:97], 0, v[0:1]
	v_cmp_eq_u32_e32 vcc, 0, v4
	v_lshl_add_u64 v[2:3], s[0:1], 0, v[2:3]
	s_mov_b64 s[10:11], 0
	s_branch .LBB0_65

.LBB0_100:
	v_readlane_b32 s10, v243, 54
	v_readlane_b32 s38, v243, 26
	v_readlane_b32 s18, v240, 53
	v_readlane_b32 s16, v243, 21
	s_mov_b64 s[12:13], -1
	s_mov_b32 s48, 0.5
	s_movk_i32 s34, 0xb00
	s_movk_i32 s47, 0x400
	s_mov_b64 s[8:9], 0
	s_mov_b32 s44, 8
	s_mov_b32 s23, 1
	s_mov_b64 s[6:7], 0
	v_readlane_b32 s11, v243, 55
	s_mov_b64 s[14:15], s[96:97]
	v_readlane_b32 s39, v243, 27
	v_readlane_b32 s19, v240, 54
	v_readlane_b32 s17, v243, 22

.Lwd_not5:
	s_cmp_lt_u32 s1, 0x80
	s_cbranch_scc1 .LBB0_445

.LBB0_379:
	v_readlane_b32 s0, v240, 23
	v_readlane_b32 s1, v243, 0
	s_cmp_eq_u32 s0, 5
	s_cbranch_scc1 .Lwd_s5
	s_sub_i32 s0, s1, 0x80
	s_movk_i32 s1, 0x80
	s_branch .Lwd_set

.LBB0_445:
	v_readlane_b32 s0, v240, 23
	v_readlane_b32 s3, v243, 0
	s_cmp_eq_u32 s0, 1
	s_cselect_b64 vcc, -1, 0
	s_cmp_eq_u32 s0, 8
	s_cselect_b64 s[0:1], -1, 0
	s_or_b64 s[0:1], s[0:1], vcc
	s_cmp_ge_u32 s3, 0x80
	s_cselect_b64 s[2:3], -1, 0
	s_and_b64 s[0:1], s[2:3], s[0:1]
	v_readlane_b32 s2, v240, 33
	v_readlane_b32 s3, v240, 34
	s_and_b64 s[0:1], s[2:3], s[0:1]
	s_andn2_b64 vcc, exec, s[0:1]
	s_cbranch_vccnz .LBB0_450
	v_mov_b32_e32 v2, v147
	v_readlane_b32 s0, v242, 6
	v_readlane_b32 s1, v242, 7
	v_ashrrev_i32_e32 v3, 31, v2
	s_mov_b64 s[8:9], s[88:89]
	v_lshl_add_u64 v[0:1], s[0:1], 0, v[2:3]
	s_mov_b64 s[0:1], 0xf0000
	s_mov_b64 s[10:11], s[90:91]
	s_mov_b64 s[12:13], s[92:93]
	s_mov_b64 s[14:15], s[94:95]
	v_cmp_gt_u64_e32 vcc, s[0:1], v[0:1]
	s_and_saveexec_b64 s[0:1], vcc
	v_readlane_b32 s80, v241, 40
	s_mov_b32 s6, 0x88888889
	v_readlane_b32 s86, v241, 46
	v_readlane_b32 s87, v241, 47
	v_readlane_b32 s88, v241, 48
	v_readlane_b32 s89, v241, 49
	v_readlane_b32 s7, v241, 30
	v_readlane_b32 s81, v241, 41
	v_readlane_b32 s82, v241, 42
	v_readlane_b32 s83, v241, 43
	v_readlane_b32 s84, v241, 44
	v_readlane_b32 s85, v241, 45
	v_readlane_b32 s90, v241, 50
	v_readlane_b32 s91, v241, 51
	v_readlane_b32 s92, v241, 52
	v_readlane_b32 s93, v241, 53
	v_readlane_b32 s94, v241, 54
	v_readlane_b32 s95, v241, 55
	s_cbranch_execz .LBB0_449
	v_readlane_b32 s2, v243, 0
	v_readlane_b32 s3, v240, 23
	s_sub_i32 s2, s2, 0x80
	s_lshl_b32 s2, s2, 9
	v_add_lshl_u32 v2, s2, v2, 2
	s_cmp_eq_u32 s3, 1
	s_cselect_b32 s2, s86, s88
	s_cselect_b32 s3, s87, s89
	s_cselect_b32 s4, s30, s38
	s_cselect_b32 s5, s31, s39
	s_add_u32 s2, s2, 0x2000
	s_addc_u32 s3, s3, 0
	v_mov_b32_e32 v3, v2
	v_mul_hi_u32 v19, v3, s6
	v_lshrrev_b32_e32 v19, 14, v19
	v_lshl_add_u32 v3, v19, 11, v3
	v_lshlrev_b32_e32 v4, 2, v3
	global_load_dwordx4 v[20:23], v4, s[2:3]
	v_add_u32_e32 v3, 0x40000, v2
	v_mul_hi_u32 v19, v3, s6
	v_lshrrev_b32_e32 v19, 14, v19
	v_lshl_add_u32 v3, v19, 11, v3
	v_lshlrev_b32_e32 v5, 2, v3
	global_load_dwordx4 v[24:27], v5, s[2:3]
	v_add_u32_e32 v3, 0x80000, v2
	v_mul_hi_u32 v19, v3, s6
	v_lshrrev_b32_e32 v19, 14, v19
	v_lshl_add_u32 v3, v19, 11, v3
	v_lshlrev_b32_e32 v6, 2, v3
	global_load_dwordx4 v[28:31], v6, s[2:3]
	v_add_u32_e32 v3, 0xc0000, v2
	v_mul_hi_u32 v19, v3, s6
	v_lshrrev_b32_e32 v19, 14, v19
	v_lshl_add_u32 v3, v19, 11, v3
	v_lshlrev_b32_e32 v7, 2, v3
	global_load_dwordx4 v[32:35], v7, s[2:3]
	v_add_u32_e32 v3, 0x100000, v2
	v_mul_hi_u32 v19, v3, s6
	v_lshrrev_b32_e32 v19, 14, v19
	v_lshl_add_u32 v3, v19, 11, v3
	v_lshlrev_b32_e32 v8, 2, v3
	global_load_dwordx4 v[36:39], v8, s[2:3]
	v_add_u32_e32 v3, 0x140000, v2
	v_mul_hi_u32 v19, v3, s6
	v_lshrrev_b32_e32 v19, 14, v19
	v_lshl_add_u32 v3, v19, 11, v3
	v_lshlrev_b32_e32 v9, 2, v3
	global_load_dwordx4 v[40:43], v9, s[2:3]
	v_add_u32_e32 v3, 0x180000, v2
	v_mul_hi_u32 v19, v3, s6
	v_lshrrev_b32_e32 v19, 14, v19
	v_lshl_add_u32 v3, v19, 11, v3
	v_lshlrev_b32_e32 v10, 2, v3
	global_load_dwordx4 v[44:47], v10, s[2:3]
	v_add_u32_e32 v3, 0x1c0000, v2
	v_mul_hi_u32 v19, v3, s6
	v_lshrrev_b32_e32 v19, 14, v19
	v_lshl_add_u32 v3, v19, 11, v3
	v_lshlrev_b32_e32 v11, 2, v3
	global_load_dwordx4 v[48:51], v11, s[2:3]
	v_add_u32_e32 v3, 0x200000, v2
	v_mul_hi_u32 v19, v3, s6
	v_lshrrev_b32_e32 v19, 14, v19
	v_lshl_add_u32 v3, v19, 11, v3
	v_lshlrev_b32_e32 v12, 2, v3
	global_load_dwordx4 v[52:55], v12, s[2:3]
	v_add_u32_e32 v3, 0x240000, v2
	v_mul_hi_u32 v19, v3, s6
	v_lshrrev_b32_e32 v19, 14, v19
	v_lshl_add_u32 v3, v19, 11, v3
	v_lshlrev_b32_e32 v13, 2, v3
	global_load_dwordx4 v[56:59], v13, s[2:3]
	v_add_u32_e32 v3, 0x280000, v2
	v_mul_hi_u32 v19, v3, s6
	v_lshrrev_b32_e32 v19, 14, v19
	v_lshl_add_u32 v3, v19, 11, v3
	v_lshlrev_b32_e32 v14, 2, v3
	global_load_dwordx4 v[60:63], v14, s[2:3]
	v_add_u32_e32 v3, 0x2c0000, v2
	v_mul_hi_u32 v19, v3, s6
	v_lshrrev_b32_e32 v19, 14, v19
	v_lshl_add_u32 v3, v19, 11, v3
	v_lshlrev_b32_e32 v15, 2, v3
	global_load_dwordx4 v[64:67], v15, s[2:3]
	v_add_u32_e32 v3, 0x300000, v2
	v_mul_hi_u32 v19, v3, s6
	v_lshrrev_b32_e32 v19, 14, v19
	v_lshl_add_u32 v3, v19, 11, v3
	v_lshlrev_b32_e32 v16, 2, v3
	global_load_dwordx4 v[68:71], v16, s[2:3]
	v_add_u32_e32 v3, 0x340000, v2
	v_mul_hi_u32 v19, v3, s6
	v_lshrrev_b32_e32 v19, 14, v19
	v_lshl_add_u32 v3, v19, 11, v3
	v_lshlrev_b32_e32 v17, 2, v3
	global_load_dwordx4 v[72:75], v17, s[2:3]
	v_add_u32_e32 v3, 0x380000, v2
	v_mul_hi_u32 v19, v3, s6
	v_lshrrev_b32_e32 v19, 14, v19
	v_lshl_add_u32 v3, v19, 11, v3
	v_lshlrev_b32_e32 v18, 2, v3
	global_load_dwordx4 v[76:79], v18, s[2:3]
	s_waitcnt vmcnt(14)
	global_store_dwordx4 v4, v[20:23], s[4:5]
	s_waitcnt vmcnt(14)
	global_store_dwordx4 v5, v[24:27], s[4:5]
	s_waitcnt vmcnt(14)
	global_store_dwordx4 v6, v[28:31], s[4:5]
	s_waitcnt vmcnt(14)
	global_store_dwordx4 v7, v[32:35], s[4:5]
	s_waitcnt vmcnt(14)
	global_store_dwordx4 v8, v[36:39], s[4:5]
	s_waitcnt vmcnt(14)
	global_store_dwordx4 v9, v[40:43], s[4:5]
	s_waitcnt vmcnt(14)
	global_store_dwordx4 v10, v[44:47], s[4:5]
	s_waitcnt vmcnt(14)
	global_store_dwordx4 v11, v[48:51], s[4:5]
	s_waitcnt vmcnt(14)
	global_store_dwordx4 v12, v[52:55], s[4:5]
	s_waitcnt vmcnt(14)
	global_store_dwordx4 v13, v[56:59], s[4:5]
	s_waitcnt vmcnt(14)
	global_store_dwordx4 v14, v[60:63], s[4:5]
	s_waitcnt vmcnt(14)
	global_store_dwordx4 v15, v[64:67], s[4:5]
	s_waitcnt vmcnt(14)
	global_store_dwordx4 v16, v[68:71], s[4:5]
	s_waitcnt vmcnt(14)
	global_store_dwordx4 v17, v[72:75], s[4:5]
	s_waitcnt vmcnt(14)
	global_store_dwordx4 v18, v[76:79], s[4:5]
